# attention tile loop: first sub-tile issues both early read groups before the accumulator init; second sub-tile initialises map 0 first so its first MFMA issues sooner
# speedup vs baseline: 1.0138x; 1.0138x over previous
; #define LAS __attribute__((address_space(3)))
; __device__ __forceinline__ void dattn_unit(LAS unsigned char* lds, int b, int h, int qb, const bf16* Q, const bf16* K, const bf16* V, bf16* YB, float lam, const float* subg, float oml, int tid) {
;     ...
;         if (t + 1 < NT) { const size_t adv = (size_t)(t + 1) * 64 * 1024; kr0 = *(const v4u*)(kg + adv); kr1 = *(const v4u*)(kg + adv + 64); vr0 = *(const v4u*)(vg + adv); vr1 = *(const v4u*)(vg + adv + 8); }
;         const LAS bf16* Ks = (const LAS bf16*)(lds + (t & 1) * AT_BUF + AT_KS); const LAS bf16* Vt = (const LAS bf16*)(lds + (t & 1) * AT_BUF + AT_VT);
;         const int kvbase = t * 64;
;         if (kvbase <= qmax) {
;     ...
; #pragma unroll
;         for (int sub = 0; sub < 2; ++sub) {
;             if (kvbase + 32 * sub > qmax) continue;
;             const bool need_bm = kvbase + 32 * sub + 31 + 113 > qmin;
;             LAS bf16x8* qsp = qs; asm volatile("" : "+v"(qsp));
;             f32x16 s0, s1;
; #pragma unroll
;             for (int r = 0; r < 16; ++r) { s0[r] = -mref[0]; s1[r] = -mref[1]; }
;             {
;                 const LAS bf16* kp = Ks + (32 * sub + ql) * 72 + hi * 8;
;                 bf16x8 ka = *(const LAS bf16x8*)kp, kb = *(const LAS bf16x8*)(kp + 64 * 72), qa = qsp[0], qb = qsp[4 * 64];
;                 __builtin_amdgcn_sched_group_barrier(0x100, 4, 0);
; #pragma unroll
;                 for (int ks = 0; ks < 4; ++ks) { bf16x8 ka2 = ka, kb2 = kb, qa2 = qa, qb2 = qb;
;                     if (ks < 3) { ka2 = *(const LAS bf16x8*)(kp + (ks + 1) * 16); kb2 = *(const LAS bf16x8*)(kp + 64 * 72 + (ks + 1) * 16); qa2 = qsp[(ks + 1) * 64]; qb2 = qsp[(4 + ks + 1) * 64];
;                         __builtin_amdgcn_sched_group_barrier(0x100, 4, 0); }
;                     s0 = __builtin_amdgcn_mfma_f32_32x32x16_bf16(ka, qa, s0, 0, 0, 0);
;                     s1 = __builtin_amdgcn_mfma_f32_32x32x16_bf16(kb, qb, s1, 0, 0, 0);
;                     __builtin_amdgcn_sched_group_barrier(0x008, 2, 0);
;                     ka = ka2; kb = kb2; qa = qa2; qb = qb2; }
;             }
.LBB0_227:
	v_lshl_add_u64 v[128:129], v[184:185], 0, s[98:99]
	v_lshl_add_u64 v[130:131], v[182:183], 0, s[100:101]
	global_load_dwordx4 v[168:171], v[128:129], off
	global_load_dwordx4 v[172:175], v[128:129], off offset:128
	s_add_i32 s18, s58, 0xffffff50
	global_load_dwordx4 v[164:167], v[130:131], off
	global_load_dwordx4 v[160:163], v[130:131], off offset:16
	s_cmp_gt_i32 s18, s35
	s_cbranch_scc1 .LBB0_226
	s_bitcmp1_b32 s59, 0
	s_cselect_b32 s18, 0x9000, 0
	s_add_i32 s38, s18, 0
	v_add3_u32 v199, s38, v208, v192
	ds_read_b128 v[138:141], v199
	ds_read_b128 v[200:203], v199 offset:9216
	ds_read_b128 v[204:207], v189
	ds_read_b128 v[218:221], v189 offset:4096
	ds_read_b128 v[222:225], v199 offset:32
	ds_read_b128 v[226:229], v199 offset:9248
	ds_read_b128 v[230:233], v189 offset:1024
	ds_read_b128 v[234:237], v189 offset:5120
	v_xor_b32_e32 v144, 0x80000000, v190
	v_xor_b32_e32 v128, 0x80000000, v191
	v_mov_b32_e32 v145, v144
	v_mov_b64_e32 v[146:147], v[144:145]
	v_mov_b64_e32 v[148:149], v[144:145]
	v_mov_b64_e32 v[150:151], v[144:145]
	v_mov_b64_e32 v[152:153], v[144:145]
	v_mov_b64_e32 v[154:155], v[144:145]
	v_mov_b64_e32 v[156:157], v[144:145]
	v_mov_b64_e32 v[158:159], v[144:145]
	v_mov_b32_e32 v129, v128
	v_mov_b64_e32 v[130:131], v[128:129]
	v_mov_b64_e32 v[132:133], v[128:129]
	v_mov_b64_e32 v[134:135], v[128:129]
	v_mov_b64_e32 v[136:137], v[128:129]
	s_waitcnt lgkmcnt(5)
	v_mfma_f32_32x32x16_bf16 v[144:159], v[138:141], v[204:207], v[144:159]
	v_mov_b64_e32 v[142:143], v[128:129]
	v_mov_b64_e32 v[138:139], v[128:129]
	v_mov_b64_e32 v[140:141], v[128:129]
	s_sub_i32 s18, s58, 32
	s_cmp_le_i32 s18, s31
	s_waitcnt lgkmcnt(4)
	v_mfma_f32_32x32x16_bf16 v[128:143], v[200:203], v[218:221], v[128:143]
	ds_read_b128 v[200:203], v199 offset:64
	ds_read_b128 v[204:207], v199 offset:9280
	ds_read_b128 v[218:221], v189 offset:2048
	ds_read_b128 v[238:241], v189 offset:6144
	s_waitcnt lgkmcnt(5)
	v_mfma_f32_32x32x16_bf16 v[144:159], v[222:225], v[230:233], v[144:159]
	s_waitcnt lgkmcnt(4)
	v_mfma_f32_32x32x16_bf16 v[128:143], v[226:229], v[234:237], v[128:143]
	ds_read_b128 v[222:225], v199 offset:96
	ds_read_b128 v[226:229], v199 offset:9312
	ds_read_b128 v[230:233], v189 offset:3072
	ds_read_b128 v[234:237], v189 offset:7168
	s_waitcnt lgkmcnt(5)
	v_mfma_f32_32x32x16_bf16 v[144:159], v[200:203], v[218:221], v[144:159]
	s_cbranch_scc0 .Lqk_diag0
	s_waitcnt lgkmcnt(1)
	v_mfma_f32_32x32x16_bf16 v[144:159], v[222:225], v[230:233], v[144:159]
	v_add3_u32 v219, s38, v193, v192
	ds_read_b128 v[212:215], v219 offset:32256
	ds_read_b128 v[220:223], v219 offset:18432
	v_mfma_f32_32x32x16_bf16 v[128:143], v[204:207], v[238:241], v[128:143]
	s_waitcnt lgkmcnt(2)
	v_mfma_f32_32x32x16_bf16 v[128:143], v[226:229], v[234:237], v[128:143]
	ds_read_b128 v[228:231], v219 offset:23040
	ds_read_b128 v[232:235], v219 offset:23072
	ds_read_b128 v[236:239], v219 offset:27648
	ds_read_b128 v[240:243], v219 offset:27680
	s_nop 1

; #define LAS __attribute__((address_space(3)))
; __device__ __forceinline__ void dattn_unit(LAS unsigned char* lds, int b, int h, int qb, const bf16* Q, const bf16* K, const bf16* V, bf16* YB, float lam, const float* subg, float oml, int tid) {
;     ...
;             if (kvbase + 32 * sub > qmax) continue;
;             const bool need_bm = kvbase + 32 * sub + 31 + 113 > qmin;
;             LAS bf16x8* qsp = qs; asm volatile("" : "+v"(qsp));
;             f32x16 s0, s1;
; #pragma unroll
;             for (int r = 0; r < 16; ++r) { s0[r] = -mref[0]; s1[r] = -mref[1]; }
;             {
;                 const LAS bf16* kp = Ks + (32 * sub + ql) * 72 + hi * 8;
;                 bf16x8 ka = *(const LAS bf16x8*)kp, kb = *(const LAS bf16x8*)(kp + 64 * 72), qa = qsp[0], qb = qsp[4 * 64];
;                 __builtin_amdgcn_sched_group_barrier(0x100, 4, 0);
; #pragma unroll
;                 for (int ks = 0; ks < 4; ++ks) { bf16x8 ka2 = ka, kb2 = kb, qa2 = qa, qb2 = qb;
;                     if (ks < 3) { ka2 = *(const LAS bf16x8*)(kp + (ks + 1) * 16); kb2 = *(const LAS bf16x8*)(kp + 64 * 72 + (ks + 1) * 16); qa2 = qsp[(ks + 1) * 64]; qb2 = qsp[(4 + ks + 1) * 64];
;                         __builtin_amdgcn_sched_group_barrier(0x100, 4, 0); }
;                     s0 = __builtin_amdgcn_mfma_f32_32x32x16_bf16(ka, qa, s0, 0, 0, 0);
;                     s1 = __builtin_amdgcn_mfma_f32_32x32x16_bf16(kb, qb, s1, 0, 0, 0);
;                     __builtin_amdgcn_sched_group_barrier(0x008, 2, 0);
;                     ka = ka2; kb = kb2; qa = qa2; qb = qb2; }
;             }
.LBB0_238:
	s_add_i32 s18, s58, 0xffffff70
	s_cmp_gt_i32 s18, s35
	s_cbranch_scc1 .LBB0_226
	v_xor_b32_e32 v144, 0x80000000, v190
	v_mov_b32_e32 v145, v144
	v_mov_b64_e32 v[146:147], v[144:145]
	v_mov_b64_e32 v[148:149], v[144:145]
	v_mov_b64_e32 v[150:151], v[144:145]
	v_mov_b64_e32 v[152:153], v[144:145]
	v_mov_b64_e32 v[154:155], v[144:145]
	v_mov_b64_e32 v[156:157], v[144:145]
	v_mov_b64_e32 v[158:159], v[144:145]
	v_xor_b32_e32 v128, 0x80000000, v191
	v_mov_b32_e32 v129, v128
	s_waitcnt lgkmcnt(5)
	v_mfma_f32_32x32x16_bf16 v[144:159], v[138:141], v[218:221], v[144:159]
	v_mov_b64_e32 v[130:131], v[128:129]
	v_mov_b64_e32 v[132:133], v[128:129]
	v_mov_b64_e32 v[134:135], v[128:129]
	v_mov_b64_e32 v[136:137], v[128:129]
	v_mov_b64_e32 v[142:143], v[128:129]
	v_mov_b64_e32 v[138:139], v[128:129]
	v_mov_b64_e32 v[140:141], v[128:129]
	s_cmp_le_i32 s58, s31
	s_waitcnt lgkmcnt(4)
	v_mfma_f32_32x32x16_bf16 v[128:143], v[204:207], v[222:225], v[128:143]
	ds_read_b128 v[204:207], v199 offset:4672
	ds_read_b128 v[218:221], v199 offset:13888
	ds_read_b128 v[222:225], v189 offset:2048
	ds_read_b128 v[212:215], v189 offset:6144
	s_waitcnt lgkmcnt(5)
	v_mfma_f32_32x32x16_bf16 v[144:159], v[226:229], v[234:237], v[144:159]
	s_waitcnt lgkmcnt(4)
	v_mfma_f32_32x32x16_bf16 v[128:143], v[230:233], v[238:241], v[128:143]
	ds_read_b128 v[226:229], v199 offset:4704
	ds_read_b128 v[230:233], v199 offset:13920
	ds_read_b128 v[234:237], v189 offset:3072
	ds_read_b128 v[238:241], v189 offset:7168
	s_waitcnt lgkmcnt(5)
	v_mfma_f32_32x32x16_bf16 v[144:159], v[204:207], v[222:225], v[144:159]
	s_cbranch_scc0 .Lqk_diag1
	s_waitcnt lgkmcnt(1)
	v_mfma_f32_32x32x16_bf16 v[144:159], v[226:229], v[234:237], v[144:159]
	v_add3_u32 v243, s38, v193, v192
	ds_read_b128 v[222:225], v243 offset:23104
	ds_read_b128 v[226:229], v243 offset:23136
	v_mfma_f32_32x32x16_bf16 v[128:143], v[218:221], v[212:215], v[128:143]
	s_waitcnt lgkmcnt(2)
	v_mfma_f32_32x32x16_bf16 v[128:143], v[230:233], v[238:241], v[128:143]
	ds_read_b128 v[230:233], v243 offset:27712
	ds_read_b128 v[234:237], v243 offset:27744
	ds_read_b128 v[238:241], v243 offset:32320
	ds_read_b128 v[212:215], v243 offset:18496
	ds_read_b128 v[200:203], v243 offset:18528
	s_nop 1
